# v_full3 + FFN-out RESID: half of the workgroups (bit 3 of id) run their split-K unit first, so the residual read-modify-write bursts of the two halves do not coincide
# baseline (speedup 1.0000x reference)
.LBB0_1817:
	s_mov_b32 s2, s39
	s_bitcmp1_b32 s95, 3
	s_cbranch_scc0 .Lmy_dsF_a
	s_cmpk_ge_u32 s95, 0xdc
	s_cbranch_scc1 .Lmy_dsF_a
	s_cmp_gt_u32 s39, 2
	s_cbranch_scc1 .Lmy_dsF_a
	s_add_i32 s2, s39, 2
	s_sub_i32 s3, s2, 3
	s_cmp_gt_u32 s2, 2
	s_cselect_b32 s2, s3, s2
.Lmy_dsF_a:
	s_cmp_ge_i32 s2, s46
	s_cselect_b64 s[4:5], -1, 0
	s_cmp_lt_i32 s2, s46
	s_cbranch_scc1 .LBB0_2053
	s_sub_i32 s2, s2, s46
	s_mul_i32 s2, s2, s38
	s_mov_b32 s3, s95
	s_add_i32 s6, s3, s2
	s_cmpk_lt_i32 s6, 0xdc
	s_cselect_b64 s[2:3], -1, 0
	s_cmpk_gt_i32 s6, 0xdb
	s_cbranch_scc1 .LBB0_2054
	s_mul_hi_i32 s7, s6, 0x2e8ba2e9
	s_ashr_i32 s8, s7, 1
	s_lshr_b32 s9, s7, 31
	s_add_i32 s8, s8, s9
	s_mul_i32 s10, s8, 11
	s_sub_i32 s14, s6, s10
	s_ashr_i32 s6, s8, 31
	s_lshr_b32 s6, s6, 30
	s_add_i32 s6, s8, s6
	s_and_b32 s6, s6, -4
	s_sub_i32 s15, s8, s6
	s_ashr_i32 s6, s7, 3
	s_add_i32 s6, s6, s9
	s_add_i32 s33, s6, 0x80
	s_lshl_b32 s6, s14, 8
	s_mov_b32 s7, 0
	s_mov_b32 s10, 4

.LBB0_2055:
	s_mov_b32 s2, s92
	s_mov_b32 s7, s39
	s_bitcmp1_b32 s95, 3
	s_cbranch_scc0 .Lmy_dsF_b
	s_cmpk_ge_u32 s95, 0xdc
	s_cbranch_scc1 .Lmy_dsF_b
	s_cmp_gt_u32 s39, 2
	s_cbranch_scc1 .Lmy_dsF_b
	s_add_i32 s7, s39, 2
	s_sub_i32 s6, s7, 3
	s_cmp_gt_u32 s7, 2
	s_cselect_b32 s7, s6, s7
.Lmy_dsF_b:
	s_ashr_i32 s3, s2, 31
	s_mul_hi_u32 s6, s2, s7
	s_mul_i32 s3, s3, s7
	s_add_i32 s3, s6, s3
	s_mov_b32 s6, s95
	s_mul_i32 s2, s2, s7
	s_ashr_i32 s7, s6, 31
	s_add_u32 s6, s2, s6
	s_addc_u32 s7, s3, s7
	v_cmp_gt_i64_e32 vcc, s[6:7], v[158:159]
	v_cmp_lt_i64_e64 s[2:3], s[6:7], v[156:157]
	s_cbranch_vccnz .LBB0_2061
	s_ashr_i32 s7, s6, 31
	s_lshr_b32 s7, s7, 29
	s_add_i32 s8, s6, s7
	s_and_b32 s7, s8, -8
	s_sub_i32 s9, s6, s7
	s_cmp_gt_i32 s9, -1
	s_mov_b64 s[6:7], -1
	s_cbranch_scc0 .LBB0_2058
	s_lshl_b32 s10, s9, 6
	s_mov_b64 s[6:7], 0
